# attention epilogue: 8 gate loads hoisted and issued together, per-block vmcnt waits removed; retention prologue vmcnt(1)
# speedup vs baseline: 1.0298x; 1.0138x over previous
.LBB0_113:
	s_lshr_b32 s6, s40, 2
	s_and_b32 s0, s6, 0x1fffffc0
	s_sub_i32 s7, s0, 64
	s_cmpk_lt_i32 s40, 0x100
	s_cselect_b64 s[0:1], -1, 0
	s_and_b64 s[0:1], s[0:1], exec
	s_cselect_b32 s0, 0, s7
	s_and_b32 s1, s6, 56
	s_or_b32 s41, s0, s1
	s_ashr_i32 s0, s41, 4
	s_lshl_b32 s1, s0, 10
	s_add_i32 s8, s1, 0x1000
	s_lshl_b32 s9, s0, 8
	s_cmpk_lt_i32 s40, 0x100
	s_cselect_b64 s[6:7], -1, 0
	s_and_b64 s[0:1], s[6:7], exec
	s_cselect_b32 s45, 8, 2
	s_cselect_b32 s48, s8, s9
	s_cmpk_gt_i32 s40, 0xff
	s_cselect_b64 s[8:9], -1, 0
	s_and_b32 s0, s40, 6
	s_or_b32 s0, s41, s0
	s_and_b32 s1, s40, 1
	s_bfe_i32 s12, s40, 0x10000
	s_bfe_u32 s44, s0, 0x30001
	s_cmp_eq_u32 s1, 0
	s_cselect_b64 s[0:1], -1, 0
	v_readlane_b32 s80, v252, 40
	s_and_b64 s[10:11], s[0:1], exec
	v_readlane_b32 s88, v252, 48
	v_readlane_b32 s89, v252, 49
	v_readlane_b32 s90, v252, 50
	v_readlane_b32 s91, v252, 51
	s_cselect_b32 s13, s89, s91
	s_cselect_b32 s14, s88, s90
	s_or_b32 s10, s44, s36
	s_ashr_i32 s11, s10, 31
	s_lshl_b64 s[10:11], s[10:11], 2
	s_add_u32 s10, s14, s10
	s_addc_u32 s11, s13, s11
	s_add_i32 s49, s45, -1
	global_load_dword v104, v145, s[10:11]
	s_lshl_b32 s10, s49, 7
	s_waitcnt vmcnt(1)
	v_sub_u32_e32 v0, 0x7f, v149
	s_and_b32 s10, s12, s10
	v_cndmask_b32_e64 v236, v0, v149, s[0:1]
	s_add_i32 s14, s48, s10
	v_add_u32_e32 v0, s14, v236
	v_mov_b64_e32 v[16:17], s[42:43]
	v_sub_u32_e32 v2, 0x7f, v191
	v_mad_i64_i32 v[0:1], s[10:11], v0, s69, v[16:17]
	s_lshl_b32 s46, s44, 9
	v_cndmask_b32_e64 v237, v2, v191, s[0:1]
	v_lshl_add_u64 v[0:1], v[0:1], 0, s[46:47]
	v_add_u32_e32 v2, s14, v237
	v_sub_u32_e32 v8, 0x7f, v192
	v_lshl_add_u64 v[0:1], v[0:1], 0, v[144:145]
	v_mad_i64_i32 v[2:3], s[10:11], v2, s69, v[16:17]
	v_cndmask_b32_e64 v238, v8, v192, s[0:1]
	v_add_co_u32_e32 v0, vcc, s68, v0
	v_lshl_add_u64 v[2:3], v[2:3], 0, s[46:47]
	v_add_u32_e32 v8, s14, v238
	v_addc_co_u32_e32 v1, vcc, 0, v1, vcc
	v_lshl_add_u64 v[2:3], v[2:3], 0, v[144:145]
	v_mad_i64_i32 v[8:9], s[10:11], v8, s69, v[16:17]
	v_cndmask_b32_e64 v239, v194, v193, s[0:1]
	v_add_co_u32_e32 v4, vcc, s68, v2
	v_lshl_add_u64 v[8:9], v[8:9], 0, s[46:47]
	v_add_u32_e32 v10, s14, v239
	v_addc_co_u32_e32 v5, vcc, 0, v3, vcc
	v_lshl_add_u64 v[8:9], v[8:9], 0, v[144:145]
	v_mad_i64_i32 v[10:11], s[10:11], v10, s69, v[16:17]
	v_cndmask_b32_e64 v240, v196, v195, s[0:1]
	v_add_co_u32_e32 v8, vcc, s68, v8
	v_lshl_add_u64 v[10:11], v[10:11], 0, s[46:47]
	v_add_u32_e32 v18, s14, v240
	v_addc_co_u32_e32 v9, vcc, 0, v9, vcc
	v_lshl_add_u64 v[10:11], v[10:11], 0, v[144:145]
	v_mad_i64_i32 v[18:19], s[10:11], v18, s69, v[16:17]
	v_cndmask_b32_e64 v241, v198, v197, s[0:1]
	v_add_co_u32_e32 v12, vcc, s68, v10
	v_lshl_add_u64 v[18:19], v[18:19], 0, s[46:47]
	v_add_u32_e32 v20, s14, v241
	v_addc_co_u32_e32 v13, vcc, 0, v11, vcc
	v_lshl_add_u64 v[18:19], v[18:19], 0, v[144:145]
	v_mad_i64_i32 v[20:21], s[10:11], v20, s69, v[16:17]
	v_add_co_u32_e32 v18, vcc, s68, v18
	v_lshl_add_u64 v[20:21], v[20:21], 0, s[46:47]
	s_nop 0
	v_addc_co_u32_e32 v19, vcc, 0, v19, vcc
	v_lshl_add_u64 v[20:21], v[20:21], 0, v[144:145]
	v_add_co_u32_e32 v20, vcc, s68, v20
	v_cndmask_b32_e64 v242, v200, v199, s[0:1]
	global_load_dwordx4 v[0:3], v[0:1], off
	s_nop 0
	global_load_dwordx4 v[4:7], v[4:5], off
	s_nop 0
	global_load_dwordx4 v[8:11], v[8:9], off
	s_nop 0
	global_load_dwordx4 v[12:15], v[12:13], off
	v_addc_co_u32_e32 v21, vcc, 0, v21, vcc
	global_load_dwordx4 v[28:31], v[18:19], off
	global_load_dwordx4 v[44:47], v[20:21], off
	v_add_u32_e32 v18, s14, v242
	v_mad_i64_i32 v[18:19], s[10:11], v18, s69, v[16:17]
	v_cndmask_b32_e64 v243, v202, v201, s[0:1]
	v_lshl_add_u64 v[18:19], v[18:19], 0, s[46:47]
	v_add_u32_e32 v20, s14, v243
	v_lshl_add_u64 v[18:19], v[18:19], 0, v[144:145]
	v_mad_i64_i32 v[20:21], s[10:11], v20, s69, v[16:17]
	v_add_co_u32_e32 v18, vcc, s68, v18
	v_lshl_add_u64 v[20:21], v[20:21], 0, s[46:47]
	s_nop 0
	v_addc_co_u32_e32 v19, vcc, 0, v19, vcc
	v_lshl_add_u64 v[20:21], v[20:21], 0, v[144:145]
	v_add_co_u32_e32 v20, vcc, s68, v20
	v_cndmask_b32_e64 v244, v204, v203, s[0:1]
	s_nop 0
	v_addc_co_u32_e32 v21, vcc, 0, v21, vcc
	global_load_dwordx4 v[56:59], v[18:19], off
	global_load_dwordx4 v[60:63], v[20:21], off
	s_lshl_b32 s10, s40, 3
	v_add_u32_e32 v18, s14, v244
	s_and_b32 s50, s10, 0xc0
	v_mad_i64_i32 v[18:19], s[10:11], v18, s69, v[16:17]
	v_cndmask_b32_e64 v245, v206, v205, s[0:1]
	v_lshl_add_u64 v[18:19], v[18:19], 0, s[46:47]
	s_lshl_b32 s10, s50, 1
	s_mov_b32 s11, s47
	v_add_u32_e32 v20, s14, v245
	v_lshl_add_u64 v[18:19], v[18:19], 0, s[10:11]
	v_mov_b32_e32 v157, v145
	v_mad_i64_i32 v[20:21], s[12:13], v20, s69, v[16:17]
	v_lshl_add_u64 v[18:19], v[18:19], 0, v[156:157]
	s_movk_i32 s15, 0x2000
	v_lshl_add_u64 v[20:21], v[20:21], 0, s[46:47]
	v_add_co_u32_e32 v18, vcc, s15, v18
	v_lshl_add_u64 v[20:21], v[20:21], 0, s[10:11]
	s_nop 0
	v_addc_co_u32_e32 v19, vcc, 0, v19, vcc
	v_lshl_add_u64 v[20:21], v[20:21], 0, v[156:157]
	v_add_co_u32_e32 v20, vcc, s15, v20
	v_mov_b32_e32 v155, v145
	s_nop 0
	v_addc_co_u32_e32 v21, vcc, 0, v21, vcc
	global_load_dwordx4 v[64:67], v[18:19], off nt
	global_load_dwordx4 v[68:71], v[20:21], off nt
	v_sub_u32_e32 v18, 0x7f, v188
	v_cndmask_b32_e64 v105, v18, v188, s[0:1]
	v_add_u32_e32 v18, s14, v105
	v_mad_i64_i32 v[16:17], s[12:13], v18, s69, v[16:17]
	v_lshl_add_u64 v[16:17], v[16:17], 0, s[46:47]
	v_lshl_add_u64 v[52:53], v[16:17], 0, v[154:155]
	global_load_dwordx4 v[16:19], v[52:53], off
	global_load_dwordx4 v[20:23], v[52:53], off offset:64
	global_load_dwordx4 v[24:27], v[52:53], off offset:128
	global_load_dwordx4 v[32:35], v[52:53], off offset:192
	global_load_dwordx4 v[36:39], v[52:53], off offset:256
	global_load_dwordx4 v[40:43], v[52:53], off offset:320
	global_load_dwordx4 v[48:51], v[52:53], off offset:384
	s_nop 0
	global_load_dwordx4 v[52:55], v[52:53], off offset:448
	s_and_b64 vcc, exec, s[8:9]
	v_lshlrev_b32_e32 v158, 2, v146
	v_readlane_b32 s81, v252, 41
	v_readlane_b32 s82, v252, 42
	v_readlane_b32 s83, v252, 43
	v_readlane_b32 s84, v252, 44
	v_readlane_b32 s85, v252, 45
	v_readlane_b32 s86, v252, 46
	v_readlane_b32 s87, v252, 47
	v_readlane_b32 s92, v252, 52
	v_readlane_b32 s93, v252, 53
	v_readlane_b32 s94, v252, 54
	v_readlane_b32 s95, v252, 55
	s_cbranch_vccnz .LBB0_115
	v_readlane_b32 s80, v253, 0
	s_and_b64 s[12:13], s[0:1], exec
	v_readlane_b32 s81, v253, 1
	s_cselect_b32 s11, s31, s81
	s_cselect_b32 s14, s30, s80
	s_and_b32 s12, s41, -16
	s_add_i32 s12, s12, s36
	s_or_b32 s12, s44, s12
	s_ashr_i32 s13, s12, 31
	s_lshl_b64 s[12:13], s[12:13], 18
	s_add_u32 s12, s14, s12
	s_addc_u32 s11, s11, s13
	s_lshl_b32 s13, s50, 2
	s_add_u32 s12, s12, s13
	s_addc_u32 s13, s11, 0
	v_mov_b32_e32 v159, v145
	v_lshl_add_u64 v[72:73], s[12:13], 0, v[158:159]
	v_lshl_add_u64 v[72:73], v[152:153], 2, v[72:73]
	global_load_dwordx4 v[100:103], v[72:73], off nt
	global_load_dwordx4 v[96:99], v[72:73], off offset:64 nt
	global_load_dwordx4 v[92:95], v[72:73], off offset:128 nt
	global_load_dwordx4 v[88:91], v[72:73], off offset:192 nt
	v_add_co_u32_e32 v72, vcc, 0x4000, v72
	v_readlane_b32 s82, v253, 2
	s_nop 0
	v_addc_co_u32_e32 v73, vcc, 0, v73, vcc
	global_load_dwordx4 v[84:87], v[72:73], off nt
	global_load_dwordx4 v[80:83], v[72:73], off offset:64 nt
	global_load_dwordx4 v[76:79], v[72:73], off offset:128 nt
	s_nop 0
	global_load_dwordx4 v[72:75], v[72:73], off offset:192 nt
	v_readlane_b32 s83, v253, 3
	v_readlane_b32 s84, v253, 4
	v_readlane_b32 s85, v253, 5
	v_readlane_b32 s86, v253, 6
	v_readlane_b32 s87, v253, 7
	v_readlane_b32 s88, v253, 8
	v_readlane_b32 s89, v253, 9
	v_readlane_b32 s90, v253, 10
	v_readlane_b32 s91, v253, 11
	v_readlane_b32 s92, v253, 12
	v_readlane_b32 s93, v253, 13
	v_readlane_b32 s94, v253, 14
	v_readlane_b32 s95, v253, 15
	s_branch .LBB0_116

.LBB0_152:
	v_and_b32_e32 v29, 64, v181
	v_readlane_b32 s0, v254, 26
	v_xor_b32_e32 v28, 16, v181
	v_add_u32_e32 v29, 64, v29
	v_readlane_b32 s1, v254, 27
	v_cmp_lt_i32_e32 vcc, v28, v29
	v_xor_b32_e32 v30, 32, v181
	s_mov_b32 s1, s47
	v_cndmask_b32_e32 v28, v181, v28, vcc
	v_cmp_lt_i32_e32 vcc, v30, v29
	s_lshl_b64 s[0:1], s[0:1], 1
	v_readlane_b32 s4, v253, 33
	v_cndmask_b32_e32 v29, v181, v30, vcc
	v_lshl_add_u64 v[30:31], v[126:127], 0, s[0:1]
	v_readlane_b32 s5, v253, 34
	s_add_u32 s0, s4, s0
	s_addc_u32 s1, s5, s1
	v_mov_b64_e32 v[32:33], s[0:1]
	v_mad_i64_i32 v[34:35], s[0:1], v204, s70, v[32:33]
	v_lshlrev_b32_e32 v144, 1, v122
	v_lshl_add_u64 v[32:33], v[30:31], 0, v[144:145]
	s_mov_b64 s[0:1], 0x2400
	v_lshl_add_u64 v[30:31], v[32:33], 0, s[0:1]
	s_movk_i32 s0, 0x2000
	v_add_co_u32_e32 v32, vcc, s0, v32
	v_lshlrev_b32_e32 v28, 2, v28
	s_nop 0
	v_addc_co_u32_e32 v33, vcc, 0, v33, vcc
	global_load_dwordx2 v[32:33], v[32:33], off offset:1024 nt
	global_load_dwordx2 v[0:1], v[30:31], off offset:32 nt
	global_load_dwordx2 v[2:3], v[30:31], off offset:64 nt
	global_load_dwordx2 v[4:5], v[30:31], off offset:96 nt
	global_load_dwordx2 v[6:7], v[30:31], off offset:128 nt
	global_load_dwordx2 v[8:9], v[30:31], off offset:160 nt
	global_load_dwordx2 v[10:11], v[30:31], off offset:192 nt
	global_load_dwordx2 v[12:13], v[30:31], off offset:224 nt
	ds_bpermute_b32 v28, v28, v205
	v_lshlrev_b32_e32 v29, 2, v29
	v_readlane_b32 s96, v254, 21
	v_readlane_b32 s97, v254, 22
	v_readlane_b32 s98, v254, 24
	s_waitcnt lgkmcnt(0)
	v_add_f32_e32 v28, v205, v28
	ds_bpermute_b32 v146, v29, v28
	v_readlane_b32 s99, v254, 23
	v_readlane_b32 s97, v254, 25
	s_mov_b64 s[38:39], 0
	s_waitcnt vmcnt(0)
	v_lshlrev_b32_e32 v29, 16, v32
	v_mul_f32_e32 v37, 0xbfb8aa3b, v29
	v_exp_f32_e32 v37, v37
	v_and_b32_e32 v32, 0xffff0000, v32
	v_lshlrev_b32_e32 v36, 16, v33
	v_and_b32_e32 v33, 0xffff0000, v33
	v_add_f32_e32 v37, 1.0, v37
	v_div_scale_f32 v38, s[0:1], v37, v37, v29
	v_rcp_f32_e32 v39, v38
	s_nop 0
	v_fma_f32 v40, -v38, v39, 1.0
	v_fmac_f32_e32 v39, v40, v39
	v_div_scale_f32 v40, vcc, v29, v37, v29
	v_mul_f32_e32 v41, v40, v39
	v_fma_f32 v42, -v38, v41, v40
	v_fmac_f32_e32 v41, v42, v39
	v_fma_f32 v38, -v38, v41, v40
	v_div_fmas_f32 v38, v38, v39, v41
	v_div_fixup_f32 v37, v38, v37, v29
	v_mul_f32_e32 v29, 0xbfb8aa3b, v32
	v_exp_f32_e32 v29, v29
	s_nop 0
	v_add_f32_e32 v29, 1.0, v29
	v_div_scale_f32 v38, s[0:1], v29, v29, v32
	v_rcp_f32_e32 v39, v38
	s_nop 0
	v_fma_f32 v40, -v38, v39, 1.0
	v_fmac_f32_e32 v39, v40, v39
	v_div_scale_f32 v40, vcc, v32, v29, v32
	v_mul_f32_e32 v41, v40, v39
	v_fma_f32 v42, -v38, v41, v40
	v_fmac_f32_e32 v41, v42, v39
	v_fma_f32 v38, -v38, v41, v40
	v_div_fmas_f32 v38, v38, v39, v41
	v_div_fixup_f32 v38, v38, v29, v32
	v_mul_f32_e32 v29, 0xbfb8aa3b, v36
	v_exp_f32_e32 v29, v29
	s_waitcnt lgkmcnt(0)
	v_pk_add_f32 v[28:29], v[28:29], v[146:147]
	s_nop 0
	v_div_scale_f32 v32, s[0:1], v29, v29, v36
	v_rcp_f32_e32 v39, v32
	s_nop 0
	v_fma_f32 v40, -v32, v39, 1.0
	v_fmac_f32_e32 v39, v40, v39
	v_div_scale_f32 v40, vcc, v36, v29, v36
	v_mul_f32_e32 v41, v40, v39
	v_fma_f32 v42, -v32, v41, v40
	v_fmac_f32_e32 v41, v42, v39
	v_fma_f32 v32, -v32, v41, v40
	v_div_fmas_f32 v32, v32, v39, v41
	v_div_fixup_f32 v29, v32, v29, v36
	v_div_scale_f32 v32, s[0:1], v28, v28, 1.0
	v_rcp_f32_e32 v36, v32
	s_nop 0
	v_fma_f32 v39, -v32, v36, 1.0
	v_fmac_f32_e32 v36, v39, v36
	v_div_scale_f32 v39, vcc, 1.0, v28, 1.0
	v_mul_f32_e32 v40, v39, v36
	v_fma_f32 v41, -v32, v40, v39
	v_fmac_f32_e32 v40, v41, v36
	v_fma_f32 v32, -v32, v40, v39
	v_div_fmas_f32 v32, v32, v36, v40
	v_div_fixup_f32 v32, v32, v28, 1.0
	v_mul_f32_e32 v28, v76, v32
	v_mul_f32_e32 v28, v28, v37
	v_mul_f32_e32 v37, 0xbfb8aa3b, v33
	v_exp_f32_e32 v37, v37
	v_mul_f32_e32 v36, v77, v32
	v_mul_f32_e32 v36, v36, v38
	v_cvt_pk_bf16_f32 v36, v28, v36
	v_add_f32_e32 v37, 1.0, v37
	v_div_scale_f32 v38, s[0:1], v37, v37, v33
	v_rcp_f32_e32 v39, v38
	v_mul_f32_e32 v28, v78, v32
	v_mul_f32_e32 v28, v28, v29
	v_mul_f32_e32 v29, v79, v32
	v_fma_f32 v40, -v38, v39, 1.0
	v_fmac_f32_e32 v39, v40, v39
	v_div_scale_f32 v40, vcc, v33, v37, v33
	v_mul_f32_e32 v41, v40, v39
	v_fma_f32 v42, -v38, v41, v40
	v_fmac_f32_e32 v41, v42, v39
	v_fma_f32 v38, -v38, v41, v40
	v_div_fmas_f32 v38, v38, v39, v41
	v_div_fixup_f32 v33, v38, v37, v33
	v_mul_f32_e32 v29, v29, v33
	v_cvt_pk_bf16_f32 v37, v28, v29
	v_lshl_add_u64 v[28:29], v[34:35], 0, v[144:145]
	v_mov_b64_e32 v[34:35], v[0:1]
	v_mul_f32_e32 v24, v24, v32
	global_store_dwordx2 v[28:29], v[36:37], off
	v_mul_f32_e32 v37, v72, v32
	v_mul_f32_e32 v25, v25, v32
	v_mul_f32_e32 v20, v20, v32
	v_mul_f32_e32 v21, v21, v32
	v_mul_f32_e32 v16, v16, v32
	v_mul_f32_e32 v17, v17, v32
	v_lshlrev_b32_e32 v33, 16, v34
	v_mul_f32_e32 v38, 0xbfb8aa3b, v33
	v_exp_f32_e32 v38, v38
	v_and_b32_e32 v34, 0xffff0000, v34
	v_lshlrev_b32_e32 v36, 16, v35
	v_and_b32_e32 v35, 0xffff0000, v35
	v_add_f32_e32 v38, 1.0, v38
	v_div_scale_f32 v39, s[0:1], v38, v38, v33
	v_rcp_f32_e32 v40, v39
	s_nop 0
	v_fma_f32 v41, -v39, v40, 1.0
	v_fmac_f32_e32 v40, v41, v40
	v_div_scale_f32 v41, vcc, v33, v38, v33
	v_mul_f32_e32 v42, v41, v40
	v_fma_f32 v43, -v39, v42, v41
	v_fmac_f32_e32 v42, v43, v40
	v_fma_f32 v39, -v39, v42, v41
	v_div_fmas_f32 v39, v39, v40, v42
	v_div_fixup_f32 v33, v39, v38, v33
	v_mul_f32_e32 v38, 0xbfb8aa3b, v34
	v_exp_f32_e32 v38, v38
	v_mul_f32_e32 v33, v37, v33
	v_mul_f32_e32 v37, v73, v32
	v_add_f32_e32 v38, 1.0, v38
	v_div_scale_f32 v39, s[0:1], v38, v38, v34
	v_rcp_f32_e32 v40, v39
	s_nop 0
	v_fma_f32 v41, -v39, v40, 1.0
	v_fmac_f32_e32 v40, v41, v40
	v_div_scale_f32 v41, vcc, v34, v38, v34
	v_mul_f32_e32 v42, v41, v40
	v_fma_f32 v43, -v39, v42, v41
	v_fmac_f32_e32 v42, v43, v40
	v_fma_f32 v39, -v39, v42, v41
	v_div_fmas_f32 v39, v39, v40, v42
	v_div_fixup_f32 v34, v39, v38, v34
	v_mul_f32_e32 v34, v37, v34
	v_mul_f32_e32 v37, 0xbfb8aa3b, v36
	v_exp_f32_e32 v37, v37
	v_cvt_pk_bf16_f32 v34, v33, v34
	v_mul_f32_e32 v33, v74, v32
	v_add_f32_e32 v37, 1.0, v37
	v_div_scale_f32 v38, s[0:1], v37, v37, v36
	v_rcp_f32_e32 v39, v38
	s_nop 0
	v_fma_f32 v40, -v38, v39, 1.0
	v_fmac_f32_e32 v39, v40, v39
	v_div_scale_f32 v40, vcc, v36, v37, v36
	v_mul_f32_e32 v41, v40, v39
	v_fma_f32 v42, -v38, v41, v40
	v_fmac_f32_e32 v41, v42, v39
	v_fma_f32 v38, -v38, v41, v40
	v_div_fmas_f32 v38, v38, v39, v41
	v_div_fixup_f32 v36, v38, v37, v36
	v_mul_f32_e32 v37, 0xbfb8aa3b, v35
	v_exp_f32_e32 v37, v37
	v_mul_f32_e32 v33, v33, v36
	v_mul_f32_e32 v36, v75, v32
	v_add_f32_e32 v37, 1.0, v37
	v_div_scale_f32 v38, s[0:1], v37, v37, v35
	v_rcp_f32_e32 v39, v38
	s_nop 0
	v_fma_f32 v40, -v38, v39, 1.0
	v_fmac_f32_e32 v39, v40, v39
	v_div_scale_f32 v40, vcc, v35, v37, v35
	v_mul_f32_e32 v41, v40, v39
	v_fma_f32 v42, -v38, v41, v40
	v_fmac_f32_e32 v41, v42, v39
	v_fma_f32 v38, -v38, v41, v40
	v_div_fmas_f32 v38, v38, v39, v41
	v_div_fixup_f32 v35, v38, v37, v35
	v_mul_f32_e32 v35, v36, v35
	v_cvt_pk_bf16_f32 v35, v33, v35
	global_store_dwordx2 v[28:29], v[34:35], off offset:32
	v_mov_b64_e32 v[34:35], v[2:3]
	v_mul_f32_e32 v37, v68, v32
	v_lshlrev_b32_e32 v33, 16, v34
	v_mul_f32_e32 v38, 0xbfb8aa3b, v33
	v_exp_f32_e32 v38, v38
	v_and_b32_e32 v34, 0xffff0000, v34
	v_lshlrev_b32_e32 v36, 16, v35
	v_and_b32_e32 v35, 0xffff0000, v35
	v_add_f32_e32 v38, 1.0, v38
	v_div_scale_f32 v39, s[0:1], v38, v38, v33
	v_rcp_f32_e32 v40, v39
	s_nop 0
	v_fma_f32 v41, -v39, v40, 1.0
	v_fmac_f32_e32 v40, v41, v40
	v_div_scale_f32 v41, vcc, v33, v38, v33
	v_mul_f32_e32 v42, v41, v40
	v_fma_f32 v43, -v39, v42, v41
	v_fmac_f32_e32 v42, v43, v40
	v_fma_f32 v39, -v39, v42, v41
	v_div_fmas_f32 v39, v39, v40, v42
	v_div_fixup_f32 v33, v39, v38, v33
	v_mul_f32_e32 v38, 0xbfb8aa3b, v34
	v_exp_f32_e32 v38, v38
	v_mul_f32_e32 v33, v37, v33
	v_mul_f32_e32 v37, v69, v32
	v_add_f32_e32 v38, 1.0, v38
	v_div_scale_f32 v39, s[0:1], v38, v38, v34
	v_rcp_f32_e32 v40, v39
	s_nop 0
	v_fma_f32 v41, -v39, v40, 1.0
	v_fmac_f32_e32 v40, v41, v40
	v_div_scale_f32 v41, vcc, v34, v38, v34
	v_mul_f32_e32 v42, v41, v40
	v_fma_f32 v43, -v39, v42, v41
	v_fmac_f32_e32 v42, v43, v40
	v_fma_f32 v39, -v39, v42, v41
	v_div_fmas_f32 v39, v39, v40, v42
	v_div_fixup_f32 v34, v39, v38, v34
	v_mul_f32_e32 v34, v37, v34
	v_mul_f32_e32 v37, 0xbfb8aa3b, v36
	v_exp_f32_e32 v37, v37
	v_cvt_pk_bf16_f32 v34, v33, v34
	v_mul_f32_e32 v33, v70, v32
	v_add_f32_e32 v37, 1.0, v37
	v_div_scale_f32 v38, s[0:1], v37, v37, v36
	v_rcp_f32_e32 v39, v38
	s_nop 0
	v_fma_f32 v40, -v38, v39, 1.0
	v_fmac_f32_e32 v39, v40, v39
	v_div_scale_f32 v40, vcc, v36, v37, v36
	v_mul_f32_e32 v41, v40, v39
	v_fma_f32 v42, -v38, v41, v40
	v_fmac_f32_e32 v41, v42, v39
	v_fma_f32 v38, -v38, v41, v40
	v_div_fmas_f32 v38, v38, v39, v41
	v_div_fixup_f32 v36, v38, v37, v36
	v_mul_f32_e32 v37, 0xbfb8aa3b, v35
	v_exp_f32_e32 v37, v37
	v_mul_f32_e32 v33, v33, v36
	v_mul_f32_e32 v36, v71, v32
	v_add_f32_e32 v37, 1.0, v37
	v_div_scale_f32 v38, s[0:1], v37, v37, v35
	v_rcp_f32_e32 v39, v38
	s_nop 0
	v_fma_f32 v40, -v38, v39, 1.0
	v_fmac_f32_e32 v39, v40, v39
	v_div_scale_f32 v40, vcc, v35, v37, v35
	v_mul_f32_e32 v41, v40, v39
	v_fma_f32 v42, -v38, v41, v40
	v_fmac_f32_e32 v41, v42, v39
	v_fma_f32 v38, -v38, v41, v40
	v_div_fmas_f32 v38, v38, v39, v41
	v_div_fixup_f32 v35, v38, v37, v35
	v_mul_f32_e32 v35, v36, v35
	v_cvt_pk_bf16_f32 v35, v33, v35
	global_store_dwordx2 v[28:29], v[34:35], off offset:64
	v_mov_b64_e32 v[34:35], v[4:5]
	v_mul_f32_e32 v37, v64, v32
	v_lshlrev_b32_e32 v33, 16, v34
	v_mul_f32_e32 v38, 0xbfb8aa3b, v33
	v_exp_f32_e32 v38, v38
	v_and_b32_e32 v34, 0xffff0000, v34
	v_lshlrev_b32_e32 v36, 16, v35
	v_and_b32_e32 v35, 0xffff0000, v35
	v_add_f32_e32 v38, 1.0, v38
	v_div_scale_f32 v39, s[0:1], v38, v38, v33
	v_rcp_f32_e32 v40, v39
	s_nop 0
	v_fma_f32 v41, -v39, v40, 1.0
	v_fmac_f32_e32 v40, v41, v40
	v_div_scale_f32 v41, vcc, v33, v38, v33
	v_mul_f32_e32 v42, v41, v40
	v_fma_f32 v43, -v39, v42, v41
	v_fmac_f32_e32 v42, v43, v40
	v_fma_f32 v39, -v39, v42, v41
	v_div_fmas_f32 v39, v39, v40, v42
	v_div_fixup_f32 v33, v39, v38, v33
	v_mul_f32_e32 v38, 0xbfb8aa3b, v34
	v_exp_f32_e32 v38, v38
	v_mul_f32_e32 v33, v37, v33
	v_mul_f32_e32 v37, v65, v32
	v_add_f32_e32 v38, 1.0, v38
	v_div_scale_f32 v39, s[0:1], v38, v38, v34
	v_rcp_f32_e32 v40, v39
	s_nop 0
	v_fma_f32 v41, -v39, v40, 1.0
	v_fmac_f32_e32 v40, v41, v40
	v_div_scale_f32 v41, vcc, v34, v38, v34
	v_mul_f32_e32 v42, v41, v40
	v_fma_f32 v43, -v39, v42, v41
	v_fmac_f32_e32 v42, v43, v40
	v_fma_f32 v39, -v39, v42, v41
	v_div_fmas_f32 v39, v39, v40, v42
	v_div_fixup_f32 v34, v39, v38, v34
	v_mul_f32_e32 v34, v37, v34
	v_mul_f32_e32 v37, 0xbfb8aa3b, v36
	v_exp_f32_e32 v37, v37
	v_cvt_pk_bf16_f32 v34, v33, v34
	v_mul_f32_e32 v33, v66, v32
	v_add_f32_e32 v37, 1.0, v37
	v_div_scale_f32 v38, s[0:1], v37, v37, v36
	v_rcp_f32_e32 v39, v38
	s_nop 0
	v_fma_f32 v40, -v38, v39, 1.0
	v_fmac_f32_e32 v39, v40, v39
	v_div_scale_f32 v40, vcc, v36, v37, v36
	v_mul_f32_e32 v41, v40, v39
	v_fma_f32 v42, -v38, v41, v40
	v_fmac_f32_e32 v41, v42, v39
	v_fma_f32 v38, -v38, v41, v40
	v_div_fmas_f32 v38, v38, v39, v41
	v_div_fixup_f32 v36, v38, v37, v36
	v_mul_f32_e32 v37, 0xbfb8aa3b, v35
	v_exp_f32_e32 v37, v37
	v_mul_f32_e32 v33, v33, v36
	v_mul_f32_e32 v36, v67, v32
	v_add_f32_e32 v37, 1.0, v37
	v_div_scale_f32 v38, s[0:1], v37, v37, v35
	v_rcp_f32_e32 v39, v38
	s_nop 0
	v_fma_f32 v40, -v38, v39, 1.0
	v_fmac_f32_e32 v39, v40, v39
	v_div_scale_f32 v40, vcc, v35, v37, v35
	v_mul_f32_e32 v41, v40, v39
	v_fma_f32 v42, -v38, v41, v40
	v_fmac_f32_e32 v41, v42, v39
	v_fma_f32 v38, -v38, v41, v40
	v_div_fmas_f32 v38, v38, v39, v41
	v_div_fixup_f32 v35, v38, v37, v35
	v_mul_f32_e32 v35, v36, v35
	v_cvt_pk_bf16_f32 v35, v33, v35
	global_store_dwordx2 v[28:29], v[34:35], off offset:96
	v_mov_b64_e32 v[34:35], v[6:7]
	v_mul_f32_e32 v37, v60, v32
	v_lshlrev_b32_e32 v33, 16, v34
	v_mul_f32_e32 v38, 0xbfb8aa3b, v33
	v_exp_f32_e32 v38, v38
	v_and_b32_e32 v34, 0xffff0000, v34
	v_lshlrev_b32_e32 v36, 16, v35
	v_and_b32_e32 v35, 0xffff0000, v35
	v_add_f32_e32 v38, 1.0, v38
	v_div_scale_f32 v39, s[0:1], v38, v38, v33
	v_rcp_f32_e32 v40, v39
	s_nop 0
	v_fma_f32 v41, -v39, v40, 1.0
	v_fmac_f32_e32 v40, v41, v40
	v_div_scale_f32 v41, vcc, v33, v38, v33
	v_mul_f32_e32 v42, v41, v40
	v_fma_f32 v43, -v39, v42, v41
	v_fmac_f32_e32 v42, v43, v40
	v_fma_f32 v39, -v39, v42, v41
	v_div_fmas_f32 v39, v39, v40, v42
	v_div_fixup_f32 v33, v39, v38, v33
	v_mul_f32_e32 v38, 0xbfb8aa3b, v34
	v_exp_f32_e32 v38, v38
	v_mul_f32_e32 v33, v37, v33
	v_mul_f32_e32 v37, v61, v32
	v_add_f32_e32 v38, 1.0, v38
	v_div_scale_f32 v39, s[0:1], v38, v38, v34
	v_rcp_f32_e32 v40, v39
	s_nop 0
	v_fma_f32 v41, -v39, v40, 1.0
	v_fmac_f32_e32 v40, v41, v40
	v_div_scale_f32 v41, vcc, v34, v38, v34
	v_mul_f32_e32 v42, v41, v40
	v_fma_f32 v43, -v39, v42, v41
	v_fmac_f32_e32 v42, v43, v40
	v_fma_f32 v39, -v39, v42, v41
	v_div_fmas_f32 v39, v39, v40, v42
	v_div_fixup_f32 v34, v39, v38, v34
	v_mul_f32_e32 v34, v37, v34
	v_mul_f32_e32 v37, 0xbfb8aa3b, v36
	v_exp_f32_e32 v37, v37
	v_cvt_pk_bf16_f32 v34, v33, v34
	v_mul_f32_e32 v33, v62, v32
	v_add_f32_e32 v37, 1.0, v37
	v_div_scale_f32 v38, s[0:1], v37, v37, v36
	v_rcp_f32_e32 v39, v38
	s_nop 0
	v_fma_f32 v40, -v38, v39, 1.0
	v_fmac_f32_e32 v39, v40, v39
	v_div_scale_f32 v40, vcc, v36, v37, v36
	v_mul_f32_e32 v41, v40, v39
	v_fma_f32 v42, -v38, v41, v40
	v_fmac_f32_e32 v41, v42, v39
	v_fma_f32 v38, -v38, v41, v40
	v_div_fmas_f32 v38, v38, v39, v41
	v_div_fixup_f32 v36, v38, v37, v36
	v_mul_f32_e32 v37, 0xbfb8aa3b, v35
	v_exp_f32_e32 v37, v37
	v_mul_f32_e32 v33, v33, v36
	v_mul_f32_e32 v36, v63, v32
	v_add_f32_e32 v37, 1.0, v37
	v_div_scale_f32 v38, s[0:1], v37, v37, v35
	v_rcp_f32_e32 v39, v38
	s_nop 0
	v_fma_f32 v40, -v38, v39, 1.0
	v_fmac_f32_e32 v39, v40, v39
	v_div_scale_f32 v40, vcc, v35, v37, v35
	v_mul_f32_e32 v41, v40, v39
	v_fma_f32 v42, -v38, v41, v40
	v_fmac_f32_e32 v41, v42, v39
	v_fma_f32 v38, -v38, v41, v40
	v_div_fmas_f32 v38, v38, v39, v41
	v_div_fixup_f32 v35, v38, v37, v35
	v_mul_f32_e32 v35, v36, v35
	v_cvt_pk_bf16_f32 v35, v33, v35
	global_store_dwordx2 v[28:29], v[34:35], off offset:128
	v_mov_b64_e32 v[34:35], v[8:9]
	v_lshlrev_b32_e32 v33, 16, v34
	v_mul_f32_e32 v37, 0xbfb8aa3b, v33
	v_exp_f32_e32 v37, v37
	v_and_b32_e32 v34, 0xffff0000, v34
	v_lshlrev_b32_e32 v36, 16, v35
	v_and_b32_e32 v35, 0xffff0000, v35
	v_add_f32_e32 v37, 1.0, v37
	v_div_scale_f32 v38, s[0:1], v37, v37, v33
	v_rcp_f32_e32 v39, v38
	s_nop 0
	v_fma_f32 v40, -v38, v39, 1.0
	v_fmac_f32_e32 v39, v40, v39
	v_div_scale_f32 v40, vcc, v33, v37, v33
	v_mul_f32_e32 v41, v40, v39
	v_fma_f32 v42, -v38, v41, v40
	v_fmac_f32_e32 v41, v42, v39
	v_fma_f32 v38, -v38, v41, v40
	v_div_fmas_f32 v38, v38, v39, v41
	v_div_fixup_f32 v33, v38, v37, v33
	v_mul_f32_e32 v24, v24, v33
	v_mul_f32_e32 v33, 0xbfb8aa3b, v34
	v_exp_f32_e32 v33, v33
	s_nop 0
	v_add_f32_e32 v33, 1.0, v33
	v_div_scale_f32 v37, s[0:1], v33, v33, v34
	v_rcp_f32_e32 v38, v37
	s_nop 0
	v_fma_f32 v39, -v37, v38, 1.0
	v_fmac_f32_e32 v38, v39, v38
	v_div_scale_f32 v39, vcc, v34, v33, v34
	v_mul_f32_e32 v40, v39, v38
	v_fma_f32 v41, -v37, v40, v39
	v_fmac_f32_e32 v40, v41, v38
	v_fma_f32 v37, -v37, v40, v39
	v_div_fmas_f32 v37, v37, v38, v40
	v_div_fixup_f32 v33, v37, v33, v34
	v_mul_f32_e32 v25, v25, v33
	v_cvt_pk_bf16_f32 v24, v24, v25
	v_mul_f32_e32 v25, v26, v32
	v_mul_f32_e32 v26, 0xbfb8aa3b, v36
	v_exp_f32_e32 v26, v26
	s_nop 0
	v_add_f32_e32 v26, 1.0, v26
	v_div_scale_f32 v33, s[0:1], v26, v26, v36
	v_rcp_f32_e32 v34, v33
	s_nop 0
	v_fma_f32 v37, -v33, v34, 1.0
	v_fmac_f32_e32 v34, v37, v34
	v_div_scale_f32 v37, vcc, v36, v26, v36
	v_mul_f32_e32 v38, v37, v34
	v_fma_f32 v39, -v33, v38, v37
	v_fmac_f32_e32 v38, v39, v34
	v_fma_f32 v33, -v33, v38, v37
	v_div_fmas_f32 v33, v33, v34, v38
	v_div_fixup_f32 v26, v33, v26, v36
	v_mul_f32_e32 v25, v25, v26
	v_mul_f32_e32 v26, v27, v32
	v_mul_f32_e32 v27, 0xbfb8aa3b, v35
	v_exp_f32_e32 v27, v27
	s_nop 0
	v_add_f32_e32 v27, 1.0, v27
	v_div_scale_f32 v33, s[0:1], v27, v27, v35
	v_rcp_f32_e32 v34, v33
	s_nop 0
	v_fma_f32 v36, -v33, v34, 1.0
	v_fmac_f32_e32 v34, v36, v34
	v_div_scale_f32 v36, vcc, v35, v27, v35
	v_mul_f32_e32 v37, v36, v34
	v_fma_f32 v38, -v33, v37, v36
	v_fmac_f32_e32 v37, v38, v34
	v_fma_f32 v33, -v33, v37, v36
	v_div_fmas_f32 v33, v33, v34, v37
	v_div_fixup_f32 v27, v33, v27, v35
	v_mul_f32_e32 v26, v26, v27
	v_cvt_pk_bf16_f32 v25, v25, v26
	global_store_dwordx2 v[28:29], v[24:25], off offset:160
	v_mov_b64_e32 v[24:25], v[10:11]
	v_lshlrev_b32_e32 v26, 16, v24
	v_mul_f32_e32 v33, 0xbfb8aa3b, v26
	v_exp_f32_e32 v33, v33
	v_and_b32_e32 v24, 0xffff0000, v24
	v_lshlrev_b32_e32 v27, 16, v25
	v_and_b32_e32 v25, 0xffff0000, v25
	v_add_f32_e32 v33, 1.0, v33
	v_div_scale_f32 v34, s[0:1], v33, v33, v26
	v_rcp_f32_e32 v35, v34
	s_nop 0
	v_fma_f32 v36, -v34, v35, 1.0
	v_fmac_f32_e32 v35, v36, v35
	v_div_scale_f32 v36, vcc, v26, v33, v26
	v_mul_f32_e32 v37, v36, v35
	v_fma_f32 v38, -v34, v37, v36
	v_fmac_f32_e32 v37, v38, v35
	v_fma_f32 v34, -v34, v37, v36
	v_div_fmas_f32 v34, v34, v35, v37
	v_div_fixup_f32 v26, v34, v33, v26
	v_mul_f32_e32 v20, v20, v26
	v_mul_f32_e32 v26, 0xbfb8aa3b, v24
	v_exp_f32_e32 v26, v26
	s_nop 0
	v_add_f32_e32 v26, 1.0, v26
	v_div_scale_f32 v33, s[0:1], v26, v26, v24
	v_rcp_f32_e32 v34, v33
	s_nop 0
	v_fma_f32 v35, -v33, v34, 1.0
	v_fmac_f32_e32 v34, v35, v34
	v_div_scale_f32 v35, vcc, v24, v26, v24
	v_mul_f32_e32 v36, v35, v34
	v_fma_f32 v37, -v33, v36, v35
	v_fmac_f32_e32 v36, v37, v34
	v_fma_f32 v33, -v33, v36, v35
	v_div_fmas_f32 v33, v33, v34, v36
	v_div_fixup_f32 v24, v33, v26, v24
	v_mul_f32_e32 v21, v21, v24
	v_cvt_pk_bf16_f32 v20, v20, v21
	v_mul_f32_e32 v21, v22, v32
	v_mul_f32_e32 v22, 0xbfb8aa3b, v27
	v_exp_f32_e32 v22, v22
	s_nop 0
	v_add_f32_e32 v22, 1.0, v22
	v_div_scale_f32 v24, s[0:1], v22, v22, v27
	v_rcp_f32_e32 v26, v24
	s_nop 0
	v_fma_f32 v33, -v24, v26, 1.0
	v_fmac_f32_e32 v26, v33, v26
	v_div_scale_f32 v33, vcc, v27, v22, v27
	v_mul_f32_e32 v34, v33, v26
	v_fma_f32 v35, -v24, v34, v33
	v_fmac_f32_e32 v34, v35, v26
	v_fma_f32 v24, -v24, v34, v33
	v_div_fmas_f32 v24, v24, v26, v34
	v_div_fixup_f32 v22, v24, v22, v27
	v_mul_f32_e32 v21, v21, v22
	v_mul_f32_e32 v22, v23, v32
	v_mul_f32_e32 v23, 0xbfb8aa3b, v25
	v_exp_f32_e32 v23, v23
	s_nop 0
	v_add_f32_e32 v23, 1.0, v23
	v_div_scale_f32 v24, s[0:1], v23, v23, v25
	v_rcp_f32_e32 v26, v24
	s_nop 0
	v_fma_f32 v27, -v24, v26, 1.0
	v_fmac_f32_e32 v26, v27, v26
	v_div_scale_f32 v27, vcc, v25, v23, v25
	v_mul_f32_e32 v33, v27, v26
	v_fma_f32 v34, -v24, v33, v27
	v_fmac_f32_e32 v33, v34, v26
	v_fma_f32 v24, -v24, v33, v27
	v_div_fmas_f32 v24, v24, v26, v33
	v_div_fixup_f32 v23, v24, v23, v25
	v_mul_f32_e32 v22, v22, v23
	v_cvt_pk_bf16_f32 v21, v21, v22
	global_store_dwordx2 v[28:29], v[20:21], off offset:192
	v_mov_b64_e32 v[20:21], v[12:13]
	v_lshlrev_b32_e32 v22, 16, v20
	v_mul_f32_e32 v24, 0xbfb8aa3b, v22
	v_exp_f32_e32 v24, v24
	v_and_b32_e32 v20, 0xffff0000, v20
	v_lshlrev_b32_e32 v23, 16, v21
	v_and_b32_e32 v21, 0xffff0000, v21
	v_add_f32_e32 v24, 1.0, v24
	v_div_scale_f32 v25, s[0:1], v24, v24, v22
	v_rcp_f32_e32 v26, v25
	s_nop 0
	v_fma_f32 v27, -v25, v26, 1.0
	v_fmac_f32_e32 v26, v27, v26
	v_div_scale_f32 v27, vcc, v22, v24, v22
	v_mul_f32_e32 v30, v27, v26
	v_fma_f32 v31, -v25, v30, v27
	v_fmac_f32_e32 v30, v31, v26
	v_fma_f32 v25, -v25, v30, v27
	v_div_fmas_f32 v25, v25, v26, v30
	v_div_fixup_f32 v22, v25, v24, v22
	v_mul_f32_e32 v16, v16, v22
	v_mul_f32_e32 v22, 0xbfb8aa3b, v20
	v_exp_f32_e32 v22, v22
	s_nop 0
	v_add_f32_e32 v22, 1.0, v22
	v_div_scale_f32 v24, s[0:1], v22, v22, v20
	v_rcp_f32_e32 v25, v24
	s_nop 0
	v_fma_f32 v26, -v24, v25, 1.0
	v_fmac_f32_e32 v25, v26, v25
	v_div_scale_f32 v26, vcc, v20, v22, v20
	v_mul_f32_e32 v27, v26, v25
	v_fma_f32 v30, -v24, v27, v26
	v_fmac_f32_e32 v27, v30, v25
	v_fma_f32 v24, -v24, v27, v26
	v_div_fmas_f32 v24, v24, v25, v27
	v_div_fixup_f32 v20, v24, v22, v20
	v_mul_f32_e32 v17, v17, v20
	v_cvt_pk_bf16_f32 v16, v16, v17
	v_mul_f32_e32 v17, v18, v32
	v_mul_f32_e32 v18, 0xbfb8aa3b, v23
	v_exp_f32_e32 v18, v18
	s_nop 0
	v_add_f32_e32 v18, 1.0, v18
	v_div_scale_f32 v20, s[0:1], v18, v18, v23
	v_rcp_f32_e32 v22, v20
	s_nop 0
	v_fma_f32 v24, -v20, v22, 1.0
	v_fmac_f32_e32 v22, v24, v22
	v_div_scale_f32 v24, vcc, v23, v18, v23
	v_mul_f32_e32 v25, v24, v22
	v_fma_f32 v26, -v20, v25, v24
	v_fmac_f32_e32 v25, v26, v22
	v_fma_f32 v20, -v20, v25, v24
	v_div_fmas_f32 v20, v20, v22, v25
	v_div_fixup_f32 v18, v20, v18, v23
	v_mul_f32_e32 v17, v17, v18
	v_mul_f32_e32 v18, v19, v32
	v_mul_f32_e32 v19, 0xbfb8aa3b, v21
	v_exp_f32_e32 v19, v19
	s_nop 0
	v_add_f32_e32 v19, 1.0, v19
	v_div_scale_f32 v20, s[0:1], v19, v19, v21
	v_rcp_f32_e32 v22, v20
	s_nop 0
	v_fma_f32 v23, -v20, v22, 1.0
	v_fmac_f32_e32 v22, v23, v22
	v_div_scale_f32 v23, vcc, v21, v19, v21
	v_mul_f32_e32 v24, v23, v22
	v_fma_f32 v25, -v20, v24, v23
	v_fmac_f32_e32 v24, v25, v22
	v_fma_f32 v20, -v20, v24, v23
	v_div_fmas_f32 v20, v20, v22, v24
	v_div_fixup_f32 v19, v20, v19, v21
	v_mul_f32_e32 v18, v18, v19
	v_cvt_pk_bf16_f32 v17, v17, v18
	global_store_dwordx2 v[28:29], v[16:17], off offset:224
